# mixer A: QK_C scale deferred into the exponent fma (max over raw accumulators, p = exp2(fma(raw, QK_C, -mx))); fast path = 21 moves + 40 max3
# speedup vs baseline: 1.0159x; 1.0068x over previous
; __device__ __forceinline__ int crow(int i, int h) { return (i & 3) + 8 * (i >> 2) + 4 * h; }
; __device__ __forceinline__ void attnA_unit(LAS unsigned char* lds, const Args& A, int unit) {
;     ...
;                 for (int kt = 0; kt < 5; ++kt)
; #pragma unroll
;                     for (int i = 0; i < 16; ++i) {
;                         const int cr = crow(i, 0);
;                         float v = S[kt][i] * QK_C + bl[32 * kt + cr + 4 * hh - ql + 32];
;                         if (edge) { const int kidx = i0 - 64 + 32 * kt + cr + 4 * hh; if (kidx < 0 || kidx >= L) v = -1e30f; }
;                         S[kt][i] = v; mxp[i & 1] = fmaxf(mxp[i & 1], v);
;                     }
;                 float mx = fmaxf(mxp[0], mxp[1]);
;                 mx = fmaxf(mx, __shfl_xor(mx, 32));
.LBB0_301:
	v_cmp_gt_i32_e32 vcc, 64, v162
	v_cmp_lt_i32_e64 s[22:23], s99, v162
	v_add_u32_e32 v165, v162, v179
	s_or_b64 vcc, vcc, s[22:23]
	s_cmp_eq_u64 vcc, 0
	s_cbranch_scc1 .LmixA_fast
	s_cmp_eq_u64 vcc, exec
	s_cbranch_scc1 .LmixA_medium
	v_cmp_lt_i32_e64 s[22:23], -1, v165
	v_cmp_gt_i32_e64 s[24:25], s87, v165
	s_waitcnt lgkmcnt(1)
	s_nop 0
	s_and_b64 s[22:23], s[22:23], s[24:25]
	v_mov_b32_e32 v167, v65
	v_add_u32_e32 v65, 1, v165
	v_cndmask_b32_e64 v166, v221, v64, s[22:23]
	v_cmp_lt_i32_e64 s[22:23], -1, v65
	v_cmp_gt_i32_e64 s[24:25], s87, v65
	v_cndmask_b32_e32 v64, v64, v166, vcc
	s_and_b64 s[22:23], s[22:23], s[24:25]
	v_add_u32_e32 v166, 2, v165
	v_cndmask_b32_e64 v65, v221, v167, s[22:23]
	v_cmp_lt_i32_e64 s[22:23], -1, v166
	v_cmp_gt_i32_e64 s[24:25], s87, v166
	s_waitcnt lgkmcnt(0)
	s_nop 0
	s_and_b64 s[22:23], s[22:23], s[24:25]
	v_cndmask_b32_e64 v166, v221, v66, s[22:23]
	v_cndmask_b32_e32 v65, v167, v65, vcc
	v_cndmask_b32_e32 v66, v66, v166, vcc
	s_nop 0
	v_mov_b32_e32 v169, v67
	v_add_u32_e32 v67, 3, v165
	v_cmp_lt_i32_e64 s[22:23], -1, v67
	v_cmp_gt_i32_e64 s[24:25], s87, v67
	s_and_b64 s[22:23], s[22:23], s[24:25]
	v_cndmask_b32_e64 v67, v221, v169, s[22:23]
	v_cndmask_b32_e32 v67, v169, v67, vcc
	s_mov_b32 s22, 0xf149f2ca
	s_nop 0
	s_waitcnt lgkmcnt(1)
	s_nop 0
	v_add_u32_e32 v166, 8, v165
	v_max3_f32 v171, v65, s22, v67
	v_cmp_lt_i32_e64 s[22:23], -1, v166
	v_cmp_gt_i32_e64 s[24:25], s87, v166
	s_and_b64 s[22:23], s[22:23], s[24:25]
	v_mov_b32_e32 v167, v69
	v_add_u32_e32 v69, 9, v165
	v_cndmask_b32_e64 v166, v221, v68, s[22:23]
	v_cmp_lt_i32_e64 s[22:23], -1, v69
	v_cmp_gt_i32_e64 s[24:25], s87, v69
	v_cndmask_b32_e32 v68, v68, v166, vcc
	s_and_b64 s[22:23], s[22:23], s[24:25]
	v_add_u32_e32 v166, 10, v165
	v_cndmask_b32_e64 v69, v221, v167, s[22:23]
	v_cmp_lt_i32_e64 s[22:23], -1, v166
	v_cmp_gt_i32_e64 s[24:25], s87, v166
	s_waitcnt lgkmcnt(0)
	s_nop 0
	s_and_b64 s[22:23], s[22:23], s[24:25]
	v_cndmask_b32_e64 v166, v221, v70, s[22:23]
	v_cndmask_b32_e32 v69, v167, v69, vcc
	v_cndmask_b32_e32 v70, v70, v166, vcc
	s_nop 0
	v_mov_b32_e32 v169, v71
	v_add_u32_e32 v71, 11, v165
	v_cmp_lt_i32_e64 s[22:23], -1, v71
	v_cmp_gt_i32_e64 s[24:25], s87, v71
	s_and_b64 s[22:23], s[22:23], s[24:25]
	v_cndmask_b32_e64 v71, v221, v169, s[22:23]
	v_cndmask_b32_e32 v71, v169, v71, vcc
	s_nop 0
	s_waitcnt lgkmcnt(1)
	s_nop 0
	v_add_u32_e32 v166, 16, v165
	v_cmp_lt_i32_e64 s[22:23], -1, v166
	v_cmp_gt_i32_e64 s[24:25], s87, v166
	s_and_b64 s[22:23], s[22:23], s[24:25]
	v_mov_b32_e32 v167, v73
	v_add_u32_e32 v73, 17, v165
	v_cndmask_b32_e64 v166, v221, v72, s[22:23]
	v_cmp_lt_i32_e64 s[22:23], -1, v73
	v_cmp_gt_i32_e64 s[24:25], s87, v73
	v_cndmask_b32_e32 v72, v72, v166, vcc
	s_and_b64 s[22:23], s[22:23], s[24:25]
	v_add_u32_e32 v166, 18, v165
	v_cndmask_b32_e64 v73, v221, v167, s[22:23]
	v_cmp_lt_i32_e64 s[22:23], -1, v166
	v_cmp_gt_i32_e64 s[24:25], s87, v166
	s_waitcnt lgkmcnt(0)
	s_nop 0
	s_and_b64 s[22:23], s[22:23], s[24:25]
	v_cndmask_b32_e64 v166, v221, v74, s[22:23]
	v_cndmask_b32_e32 v73, v167, v73, vcc
	v_cndmask_b32_e32 v74, v74, v166, vcc
	s_nop 0
	v_mov_b32_e32 v169, v75
	v_add_u32_e32 v75, 19, v165
	v_cmp_lt_i32_e64 s[22:23], -1, v75
	v_cmp_gt_i32_e64 s[24:25], s87, v75
	s_and_b64 s[22:23], s[22:23], s[24:25]
	v_cndmask_b32_e64 v75, v221, v169, s[22:23]
	v_cndmask_b32_e32 v168, v169, v75, vcc
	s_waitcnt lgkmcnt(0)
	v_mov_b32_e32 v75, v76
	v_add_u32_e32 v76, 24, v165
	v_cmp_lt_i32_e64 s[22:23], -1, v76
	v_cmp_gt_i32_e64 s[24:25], s87, v76
	v_max_f32_e32 v170, 0xf149f2ca, v64
	s_and_b64 s[22:23], s[22:23], s[24:25]
	v_max3_f32 v170, v170, v66, v68
	v_cndmask_b32_e64 v76, v221, v75, s[22:23]
	v_max3_f32 v171, v171, v69, v71
	v_max3_f32 v170, v170, v70, v72
	v_cndmask_b32_e32 v75, v75, v76, vcc
	v_max3_f32 v169, v171, v73, v168
	v_max3_f32 v172, v170, v74, v75
	s_nop 0
	v_add_u32_e32 v76, 25, v165
	v_cmp_lt_i32_e64 s[22:23], -1, v76
	v_cmp_gt_i32_e64 s[24:25], s87, v76
	v_mov_b32_e32 v167, v77
	s_and_b64 s[22:23], s[22:23], s[24:25]
	v_cndmask_b32_e64 v76, v221, v167, s[22:23]
	v_cndmask_b32_e32 v76, v167, v76, vcc
	s_nop 0
	s_waitcnt lgkmcnt(1)
	v_mov_b32_e32 v77, v78
	v_add_u32_e32 v78, 26, v165
	v_cmp_lt_i32_e64 s[22:23], -1, v78
	v_cmp_gt_i32_e64 s[24:25], s87, v78
	s_and_b64 s[22:23], s[22:23], s[24:25]
	v_cndmask_b32_e64 v78, v221, v77, s[22:23]
	v_cndmask_b32_e32 v77, v77, v78, vcc
	v_add_u32_e32 v78, 27, v165
	v_cmp_lt_i32_e64 s[22:23], -1, v78
	v_cmp_gt_i32_e64 s[24:25], s87, v78
	v_mov_b32_e32 v171, v79
	s_and_b64 s[22:23], s[22:23], s[24:25]
	v_cndmask_b32_e64 v78, v221, v171, s[22:23]
	s_waitcnt lgkmcnt(0)
	s_nop 0
	v_add_u32_e32 v166, 32, v165
	v_cndmask_b32_e32 v78, v171, v78, vcc
	v_cmp_lt_i32_e64 s[22:23], -1, v166
	v_cmp_gt_i32_e64 s[24:25], s87, v166
	s_nop 0
	s_and_b64 s[22:23], s[22:23], s[24:25]
	v_mov_b32_e32 v167, v49
	v_add_u32_e32 v49, 33, v165
	v_cndmask_b32_e64 v166, v221, v48, s[22:23]
	v_cmp_lt_i32_e64 s[22:23], -1, v49
	v_cmp_gt_i32_e64 s[24:25], s87, v49
	v_cndmask_b32_e32 v48, v48, v166, vcc
	s_and_b64 s[22:23], s[22:23], s[24:25]
	v_add_u32_e32 v166, 34, v165
	v_cndmask_b32_e64 v49, v221, v167, s[22:23]
	v_cmp_lt_i32_e64 s[22:23], -1, v166
	v_cmp_gt_i32_e64 s[24:25], s87, v166
	s_waitcnt lgkmcnt(0)
	s_nop 0
	s_and_b64 s[22:23], s[22:23], s[24:25]
	v_cndmask_b32_e64 v166, v221, v50, s[22:23]
	v_cndmask_b32_e32 v49, v167, v49, vcc
	v_cndmask_b32_e32 v50, v50, v166, vcc
	s_nop 0
	v_mov_b32_e32 v171, v51
	v_add_u32_e32 v51, 35, v165
	v_cmp_lt_i32_e64 s[22:23], -1, v51
	v_cmp_gt_i32_e64 s[24:25], s87, v51
	s_and_b64 s[22:23], s[22:23], s[24:25]
	v_cndmask_b32_e64 v51, v221, v171, s[22:23]
	v_cndmask_b32_e32 v51, v171, v51, vcc
	s_nop 0
	s_waitcnt lgkmcnt(1)
; __device__ __forceinline__ int crow(int i, int h) { return (i & 3) + 8 * (i >> 2) + 4 * h; }
; __device__ __forceinline__ void attnA_unit(LAS unsigned char* lds, const Args& A, int unit) {
;     ...
;                 for (int kt = 0; kt < 5; ++kt)
; #pragma unroll
;                     for (int i = 0; i < 16; ++i) {
;                         const int cr = crow(i, 0);
;                         float v = S[kt][i] * QK_C + bl[32 * kt + cr + 4 * hh - ql + 32];
;                         if (edge) { const int kidx = i0 - 64 + 32 * kt + cr + 4 * hh; if (kidx < 0 || kidx >= L) v = -1e30f; }
;                         S[kt][i] = v; mxp[i & 1] = fmaxf(mxp[i & 1], v);
;                     }
;                 float mx = fmaxf(mxp[0], mxp[1]);
;                 mx = fmaxf(mx, __shfl_xor(mx, 32));
	s_nop 0
	v_add_u32_e32 v166, 40, v165
	v_cmp_lt_i32_e64 s[22:23], -1, v166
	v_cmp_gt_i32_e64 s[24:25], s87, v166
	s_and_b64 s[22:23], s[22:23], s[24:25]
	v_mov_b32_e32 v167, v53
	v_add_u32_e32 v53, 41, v165
	v_cndmask_b32_e64 v166, v221, v52, s[22:23]
	v_cmp_lt_i32_e64 s[22:23], -1, v53
	v_cmp_gt_i32_e64 s[24:25], s87, v53
	v_cndmask_b32_e32 v52, v52, v166, vcc
	s_and_b64 s[22:23], s[22:23], s[24:25]
	v_add_u32_e32 v166, 42, v165
	v_cndmask_b32_e64 v53, v221, v167, s[22:23]
	v_cmp_lt_i32_e64 s[22:23], -1, v166
	v_cmp_gt_i32_e64 s[24:25], s87, v166
	s_waitcnt lgkmcnt(0)
	s_nop 0
	s_and_b64 s[22:23], s[22:23], s[24:25]
	v_cndmask_b32_e64 v166, v221, v54, s[22:23]
	v_cndmask_b32_e32 v53, v167, v53, vcc
	v_cndmask_b32_e32 v54, v54, v166, vcc
	s_nop 0
	v_mov_b32_e32 v171, v55
	v_add_u32_e32 v55, 43, v165
	v_cmp_lt_i32_e64 s[22:23], -1, v55
	v_cmp_gt_i32_e64 s[24:25], s87, v55
	s_and_b64 s[22:23], s[22:23], s[24:25]
	v_cndmask_b32_e64 v55, v221, v171, s[22:23]
	v_cndmask_b32_e32 v55, v171, v55, vcc
	s_nop 0
	s_waitcnt lgkmcnt(1)
	s_nop 0
	v_add_u32_e32 v166, 48, v165
	v_cmp_lt_i32_e64 s[22:23], -1, v166
	v_cmp_gt_i32_e64 s[24:25], s87, v166
	s_and_b64 s[22:23], s[22:23], s[24:25]
	v_mov_b32_e32 v167, v57
	v_add_u32_e32 v57, 49, v165
	v_cndmask_b32_e64 v166, v221, v56, s[22:23]
	v_cmp_lt_i32_e64 s[22:23], -1, v57
	v_cmp_gt_i32_e64 s[24:25], s87, v57
	v_cndmask_b32_e32 v56, v56, v166, vcc
	s_and_b64 s[22:23], s[22:23], s[24:25]
	v_add_u32_e32 v166, 50, v165
	v_cndmask_b32_e64 v57, v221, v167, s[22:23]
	v_cmp_lt_i32_e64 s[22:23], -1, v166
	v_cmp_gt_i32_e64 s[24:25], s87, v166
	s_waitcnt lgkmcnt(0)
	s_nop 0
	s_and_b64 s[22:23], s[22:23], s[24:25]
	v_cndmask_b32_e64 v166, v221, v58, s[22:23]
	v_cndmask_b32_e32 v57, v167, v57, vcc
	v_cndmask_b32_e32 v58, v58, v166, vcc
	s_nop 0
	v_mov_b32_e32 v171, v59
	v_add_u32_e32 v59, 51, v165
	v_cmp_lt_i32_e64 s[22:23], -1, v59
	v_cmp_gt_i32_e64 s[24:25], s87, v59
	s_and_b64 s[22:23], s[22:23], s[24:25]
	v_cndmask_b32_e64 v59, v221, v171, s[22:23]
	v_cndmask_b32_e32 v59, v171, v59, vcc
	s_nop 0
	s_waitcnt lgkmcnt(1)
	s_nop 0
	v_add_u32_e32 v166, 56, v165
	v_cmp_lt_i32_e64 s[22:23], -1, v166
	v_cmp_gt_i32_e64 s[24:25], s87, v166
	s_and_b64 s[22:23], s[22:23], s[24:25]
	v_mov_b32_e32 v167, v61
	v_add_u32_e32 v61, 57, v165
	v_cndmask_b32_e64 v166, v221, v60, s[22:23]
	v_cmp_lt_i32_e64 s[22:23], -1, v61
	v_cmp_gt_i32_e64 s[24:25], s87, v61
	s_and_b64 s[22:23], s[22:23], s[24:25]
	v_cndmask_b32_e64 v61, v221, v167, s[22:23]
	v_cndmask_b32_e32 v61, v167, v61, vcc
	v_add_u32_e32 v167, 58, v165
	v_max3_f32 v79, v169, v76, v78
	v_max3_f32 v169, v172, v77, v48
	v_cmp_lt_i32_e64 s[22:23], -1, v167
	v_cmp_gt_i32_e64 s[24:25], s87, v167
	v_max3_f32 v169, v169, v50, v52
	s_waitcnt lgkmcnt(0)
	s_nop 0
	s_and_b64 s[22:23], s[22:23], s[24:25]
	v_max3_f32 v169, v169, v54, v56
	v_cndmask_b32_e32 v60, v60, v166, vcc
	v_cndmask_b32_e64 v167, v221, v62, s[22:23]
	v_max3_f32 v166, v169, v58, v60
	v_cndmask_b32_e32 v169, v62, v167, vcc
	v_add_u32_e32 v62, 59, v165
	v_mov_b32_e32 v171, v63
	v_cmp_lt_i32_e64 s[22:23], -1, v62
	v_cmp_gt_i32_e64 s[24:25], s87, v62
	s_nop 0
	s_and_b64 s[22:23], s[22:23], s[24:25]
	v_cndmask_b32_e64 v167, v221, v171, s[22:23]
	v_cndmask_b32_e32 v208, v171, v167, vcc
	v_max3_f32 v79, v79, v49, v51
	s_waitcnt lgkmcnt(0)
	s_nop 0
	v_add_u32_e32 v62, 64, v165
	v_cmp_lt_i32_e64 s[22:23], -1, v62
	v_cmp_gt_i32_e64 s[24:25], s87, v62
	s_and_b64 s[22:23], s[22:23], s[24:25]
	v_cndmask_b32_e64 v62, v221, v32, s[22:23]
	v_cndmask_b32_e32 v209, v32, v62, vcc
	v_max3_f32 v32, v166, v169, v209
	s_nop 0
	v_mov_b32_e32 v63, v33
	v_add_u32_e32 v33, 0x41, v165
	v_cmp_lt_i32_e64 s[22:23], -1, v33
	v_cmp_gt_i32_e64 s[24:25], s87, v33
	s_and_b64 s[22:23], s[22:23], s[24:25]
	v_cndmask_b32_e64 v33, v221, v63, s[22:23]
	v_cndmask_b32_e32 v210, v63, v33, vcc
	s_nop 0
	s_waitcnt lgkmcnt(1)
	v_mov_b32_e32 v33, v34
	v_add_u32_e32 v34, 0x42, v165
	v_cmp_lt_i32_e64 s[22:23], -1, v34
	v_cmp_gt_i32_e64 s[24:25], s87, v34
	s_and_b64 s[22:23], s[22:23], s[24:25]
	v_cndmask_b32_e64 v34, v221, v33, s[22:23]
	v_cndmask_b32_e32 v33, v33, v34, vcc
	v_add_u32_e32 v34, 0x43, v165
	v_cmp_lt_i32_e64 s[22:23], -1, v34
	v_cmp_gt_i32_e64 s[24:25], s87, v34
	v_mov_b32_e32 v167, v35
	s_and_b64 s[22:23], s[22:23], s[24:25]
	s_waitcnt lgkmcnt(0)
	v_mov_b32_e32 v35, v36
	v_add_u32_e32 v36, 0x48, v165
	v_cndmask_b32_e64 v34, v221, v167, s[22:23]
	v_cmp_lt_i32_e64 s[22:23], -1, v36
	v_cmp_gt_i32_e64 s[24:25], s87, v36
	s_and_b64 s[22:23], s[22:23], s[24:25]
	v_cndmask_b32_e32 v34, v167, v34, vcc
	v_cndmask_b32_e64 v36, v221, v35, s[22:23]
	s_nop 0
	v_cndmask_b32_e32 v35, v35, v36, vcc
	v_add_u32_e32 v36, 0x49, v165
	v_cmp_lt_i32_e64 s[22:23], -1, v36
	v_cmp_gt_i32_e64 s[24:25], s87, v36
	v_mov_b32_e32 v63, v37
	s_and_b64 s[22:23], s[22:23], s[24:25]
	v_cndmask_b32_e64 v36, v221, v63, s[22:23]
	v_cndmask_b32_e32 v36, v63, v36, vcc
	s_nop 0
	s_waitcnt lgkmcnt(1)
	v_mov_b32_e32 v37, v38
	v_add_u32_e32 v38, 0x4a, v165
	v_cmp_lt_i32_e64 s[22:23], -1, v38
	v_cmp_gt_i32_e64 s[24:25], s87, v38
	s_and_b64 s[22:23], s[22:23], s[24:25]
	v_cndmask_b32_e64 v38, v221, v37, s[22:23]
	v_cndmask_b32_e32 v37, v37, v38, vcc
	v_add_u32_e32 v38, 0x4b, v165
	v_cmp_lt_i32_e64 s[22:23], -1, v38
	v_cmp_gt_i32_e64 s[24:25], s87, v38
	v_mov_b32_e32 v167, v39
	s_and_b64 s[22:23], s[22:23], s[24:25]
	s_waitcnt lgkmcnt(0)
; __device__ __forceinline__ int crow(int i, int h) { return (i & 3) + 8 * (i >> 2) + 4 * h; }
; __device__ __forceinline__ void attnA_unit(LAS unsigned char* lds, const Args& A, int unit) {
;     ...
;                 for (int kt = 0; kt < 5; ++kt)
; #pragma unroll
;                     for (int i = 0; i < 16; ++i) {
;                         const int cr = crow(i, 0);
;                         float v = S[kt][i] * QK_C + bl[32 * kt + cr + 4 * hh - ql + 32];
;                         if (edge) { const int kidx = i0 - 64 + 32 * kt + cr + 4 * hh; if (kidx < 0 || kidx >= L) v = -1e30f; }
;                         S[kt][i] = v; mxp[i & 1] = fmaxf(mxp[i & 1], v);
;                     }
;                 float mx = fmaxf(mxp[0], mxp[1]);
;                 mx = fmaxf(mx, __shfl_xor(mx, 32));
	v_mov_b32_e32 v39, v40
	v_add_u32_e32 v40, 0x50, v165
	v_cndmask_b32_e64 v38, v221, v167, s[22:23]
	v_cmp_lt_i32_e64 s[22:23], -1, v40
	v_cmp_gt_i32_e64 s[24:25], s87, v40
	s_and_b64 s[22:23], s[22:23], s[24:25]
	v_cndmask_b32_e32 v38, v167, v38, vcc
	v_cndmask_b32_e64 v40, v221, v39, s[22:23]
	s_nop 0
	v_cndmask_b32_e32 v39, v39, v40, vcc
	v_add_u32_e32 v40, 0x51, v165
	v_cmp_lt_i32_e64 s[22:23], -1, v40
	v_cmp_gt_i32_e64 s[24:25], s87, v40
	v_mov_b32_e32 v63, v41
	s_and_b64 s[22:23], s[22:23], s[24:25]
	v_cndmask_b32_e64 v40, v221, v63, s[22:23]
	v_cndmask_b32_e32 v40, v63, v40, vcc
	s_nop 0
	s_waitcnt lgkmcnt(1)
	v_mov_b32_e32 v41, v42
	v_add_u32_e32 v42, 0x52, v165
	v_cmp_lt_i32_e64 s[22:23], -1, v42
	v_cmp_gt_i32_e64 s[24:25], s87, v42
	s_and_b64 s[22:23], s[22:23], s[24:25]
	v_cndmask_b32_e64 v42, v221, v41, s[22:23]
	v_cndmask_b32_e32 v41, v41, v42, vcc
	v_add_u32_e32 v42, 0x53, v165
	v_cmp_lt_i32_e64 s[22:23], -1, v42
	v_cmp_gt_i32_e64 s[24:25], s87, v42
	v_mov_b32_e32 v167, v43
	s_and_b64 s[22:23], s[22:23], s[24:25]
	s_waitcnt lgkmcnt(0)
	v_mov_b32_e32 v43, v44
	v_add_u32_e32 v44, 0x58, v165
	v_cndmask_b32_e64 v42, v221, v167, s[22:23]
	v_cmp_lt_i32_e64 s[22:23], -1, v44
	v_cmp_gt_i32_e64 s[24:25], s87, v44
	s_and_b64 s[22:23], s[22:23], s[24:25]
	v_cndmask_b32_e32 v42, v167, v42, vcc
	v_cndmask_b32_e64 v44, v221, v43, s[22:23]
	s_nop 0
	v_cndmask_b32_e32 v43, v43, v44, vcc
	v_add_u32_e32 v44, 0x59, v165
	v_cmp_lt_i32_e64 s[22:23], -1, v44
	v_cmp_gt_i32_e64 s[24:25], s87, v44
	v_mov_b32_e32 v63, v45
	s_and_b64 s[22:23], s[22:23], s[24:25]
	v_cndmask_b32_e64 v44, v221, v63, s[22:23]
	v_cndmask_b32_e32 v44, v63, v44, vcc
	s_nop 0
	s_waitcnt lgkmcnt(1)
	v_mov_b32_e32 v45, v46
	v_add_u32_e32 v46, 0x5a, v165
	v_cmp_lt_i32_e64 s[22:23], -1, v46
	v_cmp_gt_i32_e64 s[24:25], s87, v46
	s_and_b64 s[22:23], s[22:23], s[24:25]
	v_cndmask_b32_e64 v46, v221, v45, s[22:23]
	v_cndmask_b32_e32 v45, v45, v46, vcc
	v_add_u32_e32 v46, 0x5b, v165
	v_cmp_lt_i32_e64 s[22:23], -1, v46
	v_cmp_gt_i32_e64 s[24:25], s87, v46
	v_mov_b32_e32 v167, v47
	s_and_b64 s[22:23], s[22:23], s[24:25]
	v_cndmask_b32_e64 v46, v221, v167, s[22:23]
	s_waitcnt lgkmcnt(0)
	s_nop 0
	v_add_u32_e32 v62, 0x60, v165
	v_cndmask_b32_e32 v46, v167, v46, vcc
	v_cmp_lt_i32_e64 s[22:23], -1, v62
	v_cmp_gt_i32_e64 s[24:25], s87, v62
	s_nop 0
	s_and_b64 s[22:23], s[22:23], s[24:25]
	v_mov_b32_e32 v63, v17
	v_add_u32_e32 v17, 0x61, v165
	v_cndmask_b32_e64 v62, v221, v16, s[22:23]
	v_cmp_lt_i32_e64 s[22:23], -1, v17
	v_cmp_gt_i32_e64 s[24:25], s87, v17
	v_max3_f32 v79, v79, v53, v55
	v_cndmask_b32_e32 v16, v16, v62, vcc
	s_and_b64 s[22:23], s[22:23], s[24:25]
	v_add_u32_e32 v62, 0x62, v165
	v_max3_f32 v79, v79, v57, v59
	v_cndmask_b32_e64 v17, v221, v63, s[22:23]
	v_cmp_lt_i32_e64 s[22:23], -1, v62
	v_cmp_gt_i32_e64 s[24:25], s87, v62
	v_max3_f32 v79, v79, v61, v208
	s_waitcnt lgkmcnt(0)
	s_nop 0
	s_and_b64 s[22:23], s[22:23], s[24:25]
	v_mov_b32_e32 v167, v19
	v_add_u32_e32 v19, 0x63, v165
	v_max3_f32 v79, v79, v210, v34
	v_cndmask_b32_e64 v62, v221, v18, s[22:23]
	v_cmp_lt_i32_e64 s[22:23], -1, v19
	v_cmp_gt_i32_e64 s[24:25], s87, v19
	v_max3_f32 v79, v79, v36, v38
	v_cndmask_b32_e32 v17, v63, v17, vcc
	v_cndmask_b32_e32 v18, v18, v62, vcc
	s_nop 0
	s_and_b64 s[22:23], s[22:23], s[24:25]
	v_max3_f32 v79, v79, v40, v42
	v_cndmask_b32_e64 v19, v221, v167, s[22:23]
	v_max3_f32 v47, v79, v44, v46
	v_cndmask_b32_e32 v19, v167, v19, vcc
	v_max3_f32 v79, v47, v17, v19
	v_add_u32_e32 v47, 0x68, v165
	v_cmp_lt_i32_e64 s[22:23], -1, v47
	v_cmp_gt_i32_e64 s[24:25], s87, v47
	s_nop 0
	s_waitcnt lgkmcnt(1)
	s_nop 0
	s_and_b64 s[22:23], s[22:23], s[24:25]
	v_mov_b32_e32 v63, v21
	v_add_u32_e32 v21, 0x69, v165
	v_cndmask_b32_e64 v47, v221, v20, s[22:23]
	v_cmp_lt_i32_e64 s[22:23], -1, v21
	v_cmp_gt_i32_e64 s[24:25], s87, v21
	s_and_b64 s[22:23], s[22:23], s[24:25]
	v_cndmask_b32_e64 v21, v221, v63, s[22:23]
	v_cndmask_b32_e32 v20, v20, v47, vcc
	v_cndmask_b32_e32 v47, v63, v21, vcc
	s_waitcnt lgkmcnt(0)
	v_mov_b32_e32 v21, v22
	v_add_u32_e32 v22, 0x6a, v165
	v_cmp_lt_i32_e64 s[22:23], -1, v22
	v_cmp_gt_i32_e64 s[24:25], s87, v22
	s_and_b64 s[22:23], s[22:23], s[24:25]
	v_cndmask_b32_e64 v22, v221, v21, s[22:23]
	s_nop 0
	v_cndmask_b32_e32 v211, v21, v22, vcc
	v_add_u32_e32 v21, 0x6b, v165
	v_cmp_lt_i32_e64 s[22:23], -1, v21
	v_cmp_gt_i32_e64 s[24:25], s87, v21
	v_mov_b32_e32 v167, v23
	s_and_b64 s[22:23], s[22:23], s[24:25]
	v_cndmask_b32_e64 v21, v221, v167, s[22:23]
	v_cndmask_b32_e32 v23, v167, v21, vcc
	s_nop 0
	s_waitcnt lgkmcnt(1)
	v_mov_b32_e32 v22, v24
	v_add_u32_e32 v24, 0x70, v165
	v_cmp_lt_i32_e64 s[22:23], -1, v24
	v_cmp_gt_i32_e64 s[24:25], s87, v24
	s_and_b64 s[22:23], s[22:23], s[24:25]
	v_cndmask_b32_e64 v24, v221, v22, s[22:23]
	v_cndmask_b32_e32 v22, v22, v24, vcc
	v_add_u32_e32 v24, 0x71, v165
	v_cmp_lt_i32_e64 s[22:23], -1, v24
	v_cmp_gt_i32_e64 s[24:25], s87, v24
	v_mov_b32_e32 v63, v25
	s_and_b64 s[22:23], s[22:23], s[24:25]
	s_waitcnt lgkmcnt(0)
	v_mov_b32_e32 v25, v26
	v_add_u32_e32 v26, 0x72, v165
	v_cndmask_b32_e64 v24, v221, v63, s[22:23]
	v_cmp_lt_i32_e64 s[22:23], -1, v26
	v_cmp_gt_i32_e64 s[24:25], s87, v26
	s_and_b64 s[22:23], s[22:23], s[24:25]
	v_cndmask_b32_e64 v26, v221, v25, s[22:23]
	v_cndmask_b32_e32 v24, v63, v24, vcc
	v_cndmask_b32_e32 v25, v25, v26, vcc
	v_add_u32_e32 v26, 0x73, v165
	s_nop 0
	v_cmp_lt_i32_e64 s[22:23], -1, v26
	v_cmp_gt_i32_e64 s[24:25], s87, v26
	v_mov_b32_e32 v167, v27
	s_and_b64 s[22:23], s[22:23], s[24:25]
	v_cndmask_b32_e64 v26, v221, v167, s[22:23]
	v_max3_f32 v21, v79, v47, v23
	v_cndmask_b32_e32 v27, v167, v26, vcc
	v_add_u32_e32 v26, 0x78, v165
	v_max3_f32 v79, v21, v24, v27
	s_waitcnt lgkmcnt(0)
; __device__ __forceinline__ int crow(int i, int h) { return (i & 3) + 8 * (i >> 2) + 4 * h; }
; __device__ __forceinline__ void attnA_unit(LAS unsigned char* lds, const Args& A, int unit) {
;     ...
;                 for (int kt = 0; kt < 5; ++kt)
; #pragma unroll
;                     for (int i = 0; i < 16; ++i) {
;                         const int cr = crow(i, 0);
;                         float v = S[kt][i] * QK_C + bl[32 * kt + cr + 4 * hh - ql + 32];
;                         if (edge) { const int kidx = i0 - 64 + 32 * kt + cr + 4 * hh; if (kidx < 0 || kidx >= L) v = -1e30f; }
;                         S[kt][i] = v; mxp[i & 1] = fmaxf(mxp[i & 1], v);
;                     }
;                 float mx = fmaxf(mxp[0], mxp[1]);
;                 mx = fmaxf(mx, __shfl_xor(mx, 32));
	v_mov_b32_e32 v21, v28
	v_cmp_lt_i32_e64 s[22:23], -1, v26
	v_cmp_gt_i32_e64 s[24:25], s87, v26
	v_mov_b32_e32 v63, v29
	s_nop 0
	s_and_b64 s[22:23], s[22:23], s[24:25]
	v_cndmask_b32_e64 v26, v221, v21, s[22:23]
	v_cndmask_b32_e32 v21, v21, v26, vcc
	v_add_u32_e32 v26, 0x79, v165
	v_cmp_lt_i32_e64 s[22:23], -1, v26
	v_cmp_gt_i32_e64 s[24:25], s87, v26
	s_and_b64 s[22:23], s[22:23], s[24:25]
	s_waitcnt lgkmcnt(0)
	v_mov_b32_e32 v28, v30
	v_add_u32_e32 v30, 0x7a, v165
	v_cndmask_b32_e64 v26, v221, v63, s[22:23]
	v_cmp_lt_i32_e64 s[22:23], -1, v30
	v_cmp_gt_i32_e64 s[24:25], s87, v30
	s_and_b64 s[22:23], s[22:23], s[24:25]
	v_cndmask_b32_e64 v30, v221, v28, s[22:23]
	v_cndmask_b32_e32 v28, v28, v30, vcc
	v_add_u32_e32 v30, 0x7b, v165
	v_mov_b32_e32 v29, v31
	v_cmp_lt_i32_e64 s[22:23], -1, v30
	v_cmp_gt_i32_e64 s[24:25], s87, v30
	s_nop 0
	v_max3_f32 v32, v32, v33, v35
	s_and_b64 s[22:23], s[22:23], s[24:25]
	v_max3_f32 v32, v32, v37, v39
	v_cndmask_b32_e64 v62, v221, v29, s[22:23]
	s_waitcnt lgkmcnt(0)
	s_nop 0
	v_add_u32_e32 v30, 0x80, v165
	v_cmp_lt_i32_e64 s[22:23], -1, v30
	v_cmp_gt_i32_e64 s[24:25], s87, v30
	v_max3_f32 v32, v32, v41, v43
	s_and_b64 s[22:23], s[22:23], s[24:25]
	v_max3_f32 v32, v32, v45, v16
	v_cndmask_b32_e64 v30, v221, v0, s[22:23]
	v_max3_f32 v32, v32, v18, v20
	v_cndmask_b32_e32 v223, v0, v30, vcc
	v_mov_b32_e32 v31, v1
	s_nop 0
	v_max3_f32 v32, v32, v211, v22
	v_max3_f32 v32, v32, v25, v21
	v_max3_f32 v30, v32, v28, v223
	v_add_u32_e32 v32, 0x81, v165
	v_cmp_lt_i32_e64 s[22:23], -1, v32
	v_cmp_gt_i32_e64 s[24:25], s87, v32
	s_and_b64 s[22:23], s[22:23], s[24:25]
	s_waitcnt lgkmcnt(0)
	v_mov_b32_e32 v0, v2
	v_add_u32_e32 v2, 0x82, v165
	v_cndmask_b32_e64 v32, v221, v31, s[22:23]
	v_cmp_lt_i32_e64 s[22:23], -1, v2
	v_cmp_gt_i32_e64 s[24:25], s87, v2
	s_and_b64 s[22:23], s[22:23], s[24:25]
	v_cndmask_b32_e64 v2, v221, v0, s[22:23]
	v_cndmask_b32_e32 v225, v0, v2, vcc
	v_add_u32_e32 v0, 0x83, v165
	v_mov_b32_e32 v1, v3
	v_cmp_lt_i32_e64 s[22:23], -1, v0
	v_cmp_gt_i32_e64 s[24:25], s87, v0
	s_nop 0
	s_and_b64 s[22:23], s[22:23], s[24:25]
	v_cndmask_b32_e64 v0, v221, v1, s[22:23]
	v_cndmask_b32_e32 v227, v1, v0, vcc
	v_add_u32_e32 v1, 0x88, v165
	v_cmp_lt_i32_e64 s[22:23], -1, v1
	v_cmp_gt_i32_e64 s[24:25], s87, v1
	s_waitcnt lgkmcnt(0)
	v_mov_b32_e32 v0, v4
	s_and_b64 s[22:23], s[22:23], s[24:25]
	v_cndmask_b32_e64 v1, v221, v0, s[22:23]
	v_add_u32_e32 v2, 0x89, v165
	v_cndmask_b32_e32 v228, v0, v1, vcc
	v_cmp_lt_i32_e64 s[22:23], -1, v2
	s_nop 0
	v_cmp_gt_i32_e64 s[24:25], s87, v2
	v_mov_b32_e32 v3, v5
	s_and_b64 s[22:23], s[22:23], s[24:25]
	v_cndmask_b32_e64 v2, v221, v3, s[22:23]
	v_cndmask_b32_e32 v230, v3, v2, vcc
	v_add_u32_e32 v2, 0x8a, v165
	v_cmp_lt_i32_e64 s[22:23], -1, v2
	v_cmp_gt_i32_e64 s[24:25], s87, v2
	s_waitcnt lgkmcnt(0)
	v_mov_b32_e32 v0, v6
	s_and_b64 s[22:23], s[22:23], s[24:25]
	v_cndmask_b32_e64 v2, v221, v0, s[22:23]
	v_cndmask_b32_e32 v232, v0, v2, vcc
	v_add_u32_e32 v0, 0x8b, v165
	v_cmp_lt_i32_e64 s[22:23], -1, v0
	v_cmp_gt_i32_e64 s[24:25], s87, v0
	s_nop 0
	v_mov_b32_e32 v1, v7
	s_and_b64 s[22:23], s[22:23], s[24:25]
	v_cndmask_b32_e64 v0, v221, v1, s[22:23]
	v_cndmask_b32_e32 v233, v1, v0, vcc
	v_add_u32_e32 v1, 0x90, v165
	v_cmp_lt_i32_e64 s[22:23], -1, v1
	v_cmp_gt_i32_e64 s[24:25], s87, v1
	s_waitcnt lgkmcnt(0)
	v_mov_b32_e32 v0, v8
	s_and_b64 s[22:23], s[22:23], s[24:25]
	v_cndmask_b32_e64 v1, v221, v0, s[22:23]
	v_add_u32_e32 v2, 0x91, v165
	v_cndmask_b32_e32 v231, v0, v1, vcc
	v_cmp_lt_i32_e64 s[22:23], -1, v2
	s_nop 0
	v_cmp_gt_i32_e64 s[24:25], s87, v2
	v_mov_b32_e32 v3, v9
	s_and_b64 s[22:23], s[22:23], s[24:25]
	v_cndmask_b32_e64 v2, v221, v3, s[22:23]
	v_cndmask_b32_e32 v234, v3, v2, vcc
	v_add_u32_e32 v2, 0x92, v165
	v_cmp_lt_i32_e64 s[22:23], -1, v2
	v_cmp_gt_i32_e64 s[24:25], s87, v2
	s_waitcnt lgkmcnt(0)
	v_mov_b32_e32 v0, v10
	s_and_b64 s[22:23], s[22:23], s[24:25]
	v_cndmask_b32_e64 v2, v221, v0, s[22:23]
	v_cndmask_b32_e32 v235, v0, v2, vcc
	v_add_u32_e32 v0, 0x93, v165
	v_cmp_lt_i32_e64 s[22:23], -1, v0
	v_cmp_gt_i32_e64 s[24:25], s87, v0
	s_nop 0
	v_mov_b32_e32 v1, v11
	s_and_b64 s[22:23], s[22:23], s[24:25]
	v_cndmask_b32_e64 v0, v221, v1, s[22:23]
	v_cndmask_b32_e32 v236, v1, v0, vcc
	v_add_u32_e32 v1, 0x98, v165
	v_cmp_lt_i32_e64 s[22:23], -1, v1
	v_cmp_gt_i32_e64 s[24:25], s87, v1
	s_waitcnt lgkmcnt(0)
	v_mov_b32_e32 v0, v12
	s_and_b64 s[22:23], s[22:23], s[24:25]
	v_max3_f32 v4, v30, v225, v228
	v_cndmask_b32_e64 v1, v221, v0, s[22:23]
	v_max3_f32 v4, v4, v232, v231
	v_cndmask_b32_e32 v237, v0, v1, vcc
	v_max3_f32 v2, v4, v235, v237
	v_add_u32_e32 v4, 0x99, v165
	v_cmp_lt_i32_e64 s[22:23], -1, v4
	s_nop 0
	v_cmp_gt_i32_e64 s[24:25], s87, v4
	v_mov_b32_e32 v3, v13
	s_and_b64 s[22:23], s[22:23], s[24:25]
	v_cndmask_b32_e64 v4, v221, v3, s[22:23]
	v_cndmask_b32_e32 v240, v3, v4, vcc
	v_add_u32_e32 v3, 0x9a, v165
	v_cmp_lt_i32_e64 s[22:23], -1, v3
	v_cmp_gt_i32_e64 s[24:25], s87, v3
	s_waitcnt lgkmcnt(0)
	v_mov_b32_e32 v0, v14
	s_and_b64 s[22:23], s[22:23], s[24:25]
	v_cndmask_b32_e64 v3, v221, v0, s[22:23]
	v_cndmask_b32_e32 v26, v63, v26, vcc
	v_cndmask_b32_e32 v224, v29, v62, vcc
	v_cndmask_b32_e32 v239, v0, v3, vcc
	v_add_u32_e32 v0, 0x9b, v165
	v_max3_f32 v29, v79, v26, v224
	v_cndmask_b32_e32 v226, v31, v32, vcc
	v_cmp_lt_i32_e64 s[22:23], -1, v0
	v_cmp_gt_i32_e64 s[24:25], s87, v0
	v_max3_f32 v29, v29, v226, v227
	v_mov_b32_e32 v1, v15
	s_and_b64 s[22:23], s[22:23], s[24:25]
	v_max3_f32 v5, v29, v230, v233
	v_cndmask_b32_e64 v0, v221, v1, s[22:23]
	v_max3_f32 v5, v5, v234, v236
	v_cndmask_b32_e32 v241, v1, v0, vcc
	v_max3_f32 v0, v5, v240, v241
	v_max3_f32 v0, v2, v239, v0
	v_mov_b32_e32 v29, v26
	v_mov_b32_e32 v26, v25
	v_mov_b32_e32 v25, v24
	v_mov_b32_e32 v24, v22
	v_mov_b32_e32 v30, v28
	v_mov_b32_e32 v28, v21
	v_mov_b32_e32 v21, v47
	v_mov_b32_e32 v47, v46
	v_mov_b32_e32 v46, v45
	v_mov_b32_e32 v45, v44
	v_mov_b32_e32 v44, v43
	v_mov_b32_e32 v43, v42
	v_mov_b32_e32 v42, v41
	v_mov_b32_e32 v41, v40
	v_mov_b32_e32 v40, v39
	v_mov_b32_e32 v39, v38
	v_mov_b32_e32 v38, v37
	v_mov_b32_e32 v37, v36
	v_mov_b32_e32 v36, v35
	v_mov_b32_e32 v35, v34
	v_mov_b32_e32 v34, v33
	v_mov_b32_e32 v79, v78
	v_mov_b32_e32 v78, v77
	v_mov_b32_e32 v77, v76
	v_mov_b32_e32 v76, v75
	v_mov_b32_e32 v33, v210
	v_mov_b32_e32 v22, v211
	s_branch .LmixA_join

; __device__ __forceinline__ int crow(int i, int h) { return (i & 3) + 8 * (i >> 2) + 4 * h; }
; __device__ __forceinline__ void attnA_unit(LAS unsigned char* lds, const Args& A, int unit) {
;     ...
;                 const bool edge = (i0 < 64) || (i0 + 96 > L);
;                 float mxp[2] = {-1e30f, -1e30f};
; #pragma unroll
;                 for (int kt = 0; kt < 5; ++kt)
; #pragma unroll
;                     for (int i = 0; i < 16; ++i) {
;                         const int cr = crow(i, 0);
;                         float v = S[kt][i] * QK_C + bl[32 * kt + cr + 4 * hh - ql + 32];
;                         if (edge) { const int kidx = i0 - 64 + 32 * kt + cr + 4 * hh; if (kidx < 0 || kidx >= L) v = -1e30f; }
;                         S[kt][i] = v; mxp[i & 1] = fmaxf(mxp[i & 1], v);
;                     }
;                 float mx = fmaxf(mxp[0], mxp[1]);
;                 mx = fmaxf(mx, __shfl_xor(mx, 32));
;                 float lsp[2] = {0.f, 0.f};
; #pragma unroll
;                 for (int kt = 0; kt < 5; ++kt)
; #pragma unroll
;                     for (int i = 0; i < 16; ++i) { const float p = __builtin_amdgcn_exp2f(S[kt][i] - mx); S[kt][i] = p; lsp[i & 1] += p; }
.LmixA_fast:
	s_nop 7
	s_nop 3
	v_mov_b32_e32 v169, v62
	v_mov_b32_e32 v208, v63
	v_mov_b32_e32 v168, v75
	v_mov_b32_e32 v209, v32
	v_mov_b32_e32 v224, v31
	v_mov_b32_e32 v223, v0
	v_mov_b32_e32 v226, v1
	v_mov_b32_e32 v225, v2
	v_mov_b32_e32 v227, v3
	v_mov_b32_e32 v228, v4
	v_mov_b32_e32 v230, v5
	v_mov_b32_e32 v232, v6
	v_mov_b32_e32 v233, v7
	v_mov_b32_e32 v231, v8
	v_mov_b32_e32 v234, v9
	v_mov_b32_e32 v235, v10
	v_mov_b32_e32 v236, v11
	v_mov_b32_e32 v237, v12
	v_mov_b32_e32 v240, v13
	v_mov_b32_e32 v239, v14
	v_mov_b32_e32 v241, v15
	v_max3_f32 v166, v64, v65, v66
	v_max3_f32 v167, v67, v68, v69
	v_max3_f32 v166, v166, v70, v71
	v_max3_f32 v167, v167, v72, v73
	v_max3_f32 v166, v166, v74, v168
	v_max3_f32 v167, v167, v76, v77
	v_max3_f32 v166, v166, v78, v79
	v_max3_f32 v167, v167, v48, v49
	v_max3_f32 v166, v166, v50, v51
	v_max3_f32 v167, v167, v52, v53
	v_max3_f32 v166, v166, v54, v55
	v_max3_f32 v167, v167, v56, v57
	v_max3_f32 v166, v166, v58, v59
	v_max3_f32 v167, v167, v60, v61
	v_max3_f32 v166, v166, v169, v208
	v_max3_f32 v167, v167, v209, v33
	v_max3_f32 v166, v166, v34, v35
	v_max3_f32 v167, v167, v36, v37
	v_max3_f32 v166, v166, v38, v39
	v_max3_f32 v167, v167, v40, v41
	v_max3_f32 v166, v166, v42, v43
	v_max3_f32 v167, v167, v44, v45
	v_max3_f32 v166, v166, v46, v47
	v_max3_f32 v167, v167, v223, v226
	v_max3_f32 v166, v166, v225, v227
	v_max3_f32 v167, v167, v228, v230
	v_max3_f32 v166, v166, v232, v233
	v_max3_f32 v167, v167, v231, v234
	v_max3_f32 v166, v166, v235, v236
	v_max3_f32 v167, v167, v237, v240
	v_max3_f32 v166, v166, v239, v241
	v_max3_f32 v167, v167, v16, v17
	v_max3_f32 v166, v166, v18, v19
	v_max3_f32 v167, v167, v20, v21
	v_max3_f32 v166, v166, v22, v23
	v_max3_f32 v167, v167, v24, v25
	v_max3_f32 v166, v166, v26, v27
	v_max3_f32 v167, v167, v28, v29
	v_max3_f32 v166, v166, v30, v224
	v_max_f32_e32 v0, v166, v167
.LmixA_join:
	v_and_b32_e32 v2, 64, v217
	v_xor_b32_e32 v1, 32, v217
	v_add_u32_e32 v2, 64, v2
	v_cmp_lt_i32_e32 vcc, v1, v2
	v_lshlrev_b32_e32 v32, v206, v164
	s_nop 0
	v_cndmask_b32_e32 v1, v217, v1, vcc
	v_lshlrev_b32_e32 v238, 2, v1
	ds_bpermute_b32 v1, v238, v0
	s_waitcnt lgkmcnt(0)
	v_max_f32_e32 v1, v1, v1
	v_max_f32_e32 v229, v0, v1
	v_mul_f32_e32 v229, 0x3e38aa3b, v229
	v_mov_b32_e32 v252, 0x3e38aa3b
	v_fma_f32 v10, v76, v252, -v229
	v_exp_f32_e32 v172, v10
	v_fma_f32 v10, v77, v252, -v229
	v_exp_f32_e32 v173, v10
	v_fma_f32 v10, v78, v252, -v229
	v_exp_f32_e32 v174, v10
	v_fma_f32 v10, v79, v252, -v229
	v_exp_f32_e32 v175, v10
	v_fma_f32 v10, v48, v252, -v229
	v_fma_f32 v8, v72, v252, -v229
	v_exp_f32_e32 v72, v10
	v_fma_f32 v10, v49, v252, -v229
	v_exp_f32_e32 v166, v8
	v_fma_f32 v8, v73, v252, -v229
	v_exp_f32_e32 v73, v10
	v_fma_f32 v10, v50, v252, -v229
	v_exp_f32_e32 v167, v8
	v_fma_f32 v8, v74, v252, -v229
	v_exp_f32_e32 v74, v10
	v_fma_f32 v10, v51, v252, -v229
	v_exp_f32_e32 v75, v10
	v_fma_f32 v10, v52, v252, -v229
	v_exp_f32_e32 v76, v10
	v_fma_f32 v10, v53, v252, -v229
	v_exp_f32_e32 v77, v10
	v_fma_f32 v10, v54, v252, -v229
	v_exp_f32_e32 v78, v10
	v_fma_f32 v10, v55, v252, -v229
	v_exp_f32_e32 v79, v10
	v_fma_f32 v10, v56, v252, -v229
	v_exp_f32_e32 v62, v10
	v_fma_f32 v10, v57, v252, -v229
	v_exp_f32_e32 v63, v10
	v_fma_f32 v10, v58, v252, -v229
	v_fma_f32 v2, v66, v252, -v229
	v_exp_f32_e32 v66, v10
	v_fma_f32 v10, v59, v252, -v229
	v_fma_f32 v0, v64, v252, -v229
	v_fma_f32 v1, v65, v252, -v229
	v_fma_f32 v3, v67, v252, -v229
	v_exp_f32_e32 v67, v10
	v_fma_f32 v10, v60, v252, -v229
	v_exp_f32_e32 v0, v0
	v_exp_f32_e32 v1, v1
	v_fma_f32 v4, v68, v252, -v229
	v_exp_f32_e32 v68, v10
	v_fma_f32 v10, v61, v252, -v229
	v_exp_f32_e32 v2, v2
	v_exp_f32_e32 v3, v3
	v_fma_f32 v5, v69, v252, -v229
	v_exp_f32_e32 v69, v10
	v_fma_f32 v10, v169, v252, -v229
	v_exp_f32_e32 v4, v4
	v_exp_f32_e32 v5, v5
	v_fma_f32 v6, v70, v252, -v229
	v_fma_f32 v7, v71, v252, -v229
	v_exp_f32_e32 v70, v10
	v_fma_f32 v10, v208, v252, -v229
	v_exp_f32_e32 v6, v6
	v_exp_f32_e32 v7, v7
	v_exp_f32_e32 v170, v8
	v_fma_f32 v8, v168, v252, -v229
	v_exp_f32_e32 v71, v10
	v_fma_f32 v10, v209, v252, -v229
	v_exp_f32_e32 v171, v8
	v_pk_add_f32 v[8:9], v[0:1], 0 op_sel_hi:[1,0]
	v_exp_f32_e32 v54, v10
	v_fma_f32 v10, v33, v252, -v229
	v_pk_add_f32 v[8:9], v[2:3], v[8:9]
	v_exp_f32_e32 v55, v10
	v_fma_f32 v10, v34, v252, -v229
	v_pk_add_f32 v[8:9], v[4:5], v[8:9]
	v_exp_f32_e32 v58, v10
	v_fma_f32 v10, v35, v252, -v229
	v_pk_add_f32 v[8:9], v[6:7], v[8:9]
	v_exp_f32_e32 v59, v10
	v_fma_f32 v10, v36, v252, -v229
	v_pk_add_f32 v[8:9], v[166:167], v[8:9]
	v_exp_f32_e32 v60, v10
	v_fma_f32 v10, v37, v252, -v229
	v_pk_add_f32 v[8:9], v[170:171], v[8:9]
	v_exp_f32_e32 v61, v10
	v_fma_f32 v10, v38, v252, -v229
	v_pk_add_f32 v[8:9], v[172:173], v[8:9]
	v_exp_f32_e32 v64, v10
	v_fma_f32 v10, v39, v252, -v229
	v_pk_add_f32 v[8:9], v[174:175], v[8:9]
	v_exp_f32_e32 v65, v10
	v_fma_f32 v10, v40, v252, -v229
	v_pk_add_f32 v[8:9], v[72:73], v[8:9]
	v_exp_f32_e32 v48, v10
	v_fma_f32 v10, v41, v252, -v229
	v_pk_add_f32 v[8:9], v[74:75], v[8:9]
	v_exp_f32_e32 v49, v10
	v_fma_f32 v10, v42, v252, -v229
	v_pk_add_f32 v[8:9], v[76:77], v[8:9]
	v_exp_f32_e32 v50, v10
	v_fma_f32 v10, v43, v252, -v229
	v_pk_add_f32 v[8:9], v[78:79], v[8:9]
	v_exp_f32_e32 v51, v10
	v_fma_f32 v10, v44, v252, -v229
	v_pk_add_f32 v[8:9], v[62:63], v[8:9]
	v_exp_f32_e32 v52, v10
	v_fma_f32 v10, v45, v252, -v229
	v_pk_add_f32 v[8:9], v[66:67], v[8:9]
	v_exp_f32_e32 v53, v10
	v_fma_f32 v10, v46, v252, -v229
	v_pk_add_f32 v[8:9], v[68:69], v[8:9]
	v_exp_f32_e32 v56, v10
	v_fma_f32 v10, v47, v252, -v229
	v_pk_add_f32 v[8:9], v[70:71], v[8:9]
	v_exp_f32_e32 v57, v10
; #define LAS __attribute__((address_space(3)))
; #define MFMA32(a, b, c) __builtin_amdgcn_mfma_f32_32x32x16_bf16((a), (b), (c), 0, 0, 0)
; __device__ __forceinline__ s16x4 lds_tr(const LAS unsigned char* p) { return __builtin_bit_cast(s16x4, __builtin_amdgcn_ds_read_tr16_b64_v4i16((LAS v4i16_t*)p)); }
; __device__ __forceinline__ void attnA_unit(LAS unsigned char* lds, const Args& A, int unit) {
;     ...
;                 for (int kt = 0; kt < 5; ++kt)
; #pragma unroll
;                     for (int i = 0; i < 16; ++i) { const float p = __builtin_amdgcn_exp2f(S[kt][i] - mx); S[kt][i] = p; lsp[i & 1] += p; }
;                 float ls = lsp[0] + lsp[1];
;                 ls += __shfl_xor(ls, 32);
;                 f32x16 o0, o1;
; #pragma unroll
;                 for (int i = 0; i < 16; ++i) { o0[i] = 0.f; o1[i] = 0.f; }
;                 const LAS unsigned char* vr0 = vt_l + (rb + 4 * hh + ((lane & 15) >> 2)) * AST + 32 * ((lane >> 4) & 1) + 8 * (lane & 3);
; #pragma unroll
;                 for (int kt = 0; kt < 5; ++kt)
; #pragma unroll
;                     for (int ks = 0; ks < 2; ++ks) {
;                         const bf16x8 pf = pack_frag(S[kt], ks);
;                         const LAS unsigned char* vr = vr0 + (32 * kt + 16 * ks) * AST;
;                         const s16x4 a0 = lds_tr(vr), a1 = lds_tr(vr + 8 * AST), c0 = lds_tr(vr + 64), c1 = lds_tr(vr + 8 * AST + 64);
;                         o0 = MFMA32(__builtin_shufflevector(a0, a1, 0, 1, 2, 3, 4, 5, 6, 7), pf, o0);
;                         o1 = MFMA32(__builtin_shufflevector(c0, c1, 0, 1, 2, 3, 4, 5, 6, 7), pf, o1);
;                     }
	v_fma_f32 v10, v16, v252, -v229
	v_pk_add_f32 v[8:9], v[54:55], v[8:9]
	v_exp_f32_e32 v38, v10
	v_fma_f32 v10, v17, v252, -v229
	v_exp_f32_e32 v39, v10
	v_fma_f32 v10, v18, v252, -v229
	v_pk_add_f32 v[8:9], v[58:59], v[8:9]
	v_exp_f32_e32 v40, v10
	v_fma_f32 v10, v19, v252, -v229
	v_pk_add_f32 v[8:9], v[60:61], v[8:9]
	v_exp_f32_e32 v41, v10
	v_fma_f32 v10, v20, v252, -v229
	v_pk_add_f32 v[8:9], v[64:65], v[8:9]
	v_exp_f32_e32 v42, v10
	v_fma_f32 v10, v21, v252, -v229
	v_pk_add_f32 v[8:9], v[48:49], v[8:9]
	v_exp_f32_e32 v43, v10
	v_fma_f32 v10, v22, v252, -v229
	v_pk_add_f32 v[8:9], v[50:51], v[8:9]
	v_exp_f32_e32 v44, v10
	v_fma_f32 v10, v23, v252, -v229
	v_pk_add_f32 v[8:9], v[52:53], v[8:9]
	v_exp_f32_e32 v45, v10
	v_pk_add_f32 v[8:9], v[56:57], v[8:9]
	v_fma_f32 v12, v27, v252, -v229
	v_pk_add_f32 v[8:9], v[38:39], v[8:9]
	v_cvt_pk_bf16_f32 v16, v0, v1
	v_pk_add_f32 v[8:9], v[40:41], v[8:9]
	v_cvt_pk_bf16_f32 v17, v2, v3
	v_pk_add_f32 v[8:9], v[42:43], v[8:9]
	v_cvt_pk_bf16_f32 v18, v4, v5
	v_pk_add_f32 v[46:47], v[44:45], v[8:9]
	v_fma_f32 v8, v24, v252, -v229
	v_exp_f32_e32 v34, v8
	v_fma_f32 v8, v25, v252, -v229
	v_exp_f32_e32 v35, v8
	v_fma_f32 v8, v26, v252, -v229
	v_exp_f32_e32 v36, v8
	v_add_u32_e32 v8, v180, v163
	v_mad_u64_u32 v[246:247], s[22:23], v8, s88, v[152:153]
	ds_read_b64_tr_b16 v[8:9], v246 offset:59392
	ds_read_b64_tr_b16 v[10:11], v246 offset:60544
	v_cvt_pk_bf16_f32 v19, v6, v7
	v_exp_f32_e32 v37, v12
	v_fma_f32 v24, v28, v252, -v229
	ds_read_b64_tr_b16 v[20:21], v246 offset:59456
	ds_read_b64_tr_b16 v[22:23], v246 offset:60608
	s_waitcnt lgkmcnt(2)
	v_mfma_f32_32x32x16_bf16 v[0:15], v[8:11], v[16:19], 0
	v_exp_f32_e32 v164, v24
	v_fma_f32 v24, v29, v252, -v229
	ds_read_b64_tr_b16 v[208:209], v246 offset:61696
	ds_read_b64_tr_b16 v[210:211], v246 offset:62848
	v_exp_f32_e32 v165, v24
	v_fma_f32 v24, v30, v252, -v229
	v_exp_f32_e32 v168, v24
	v_cvt_pk_bf16_f32 v242, v166, v167
	s_waitcnt lgkmcnt(2)
	v_mfma_f32_32x32x16_bf16 v[16:31], v[20:23], v[16:19], 0
	v_cvt_pk_bf16_f32 v243, v170, v171
	v_cvt_pk_bf16_f32 v244, v172, v173
	v_cvt_pk_bf16_f32 v245, v174, v175
	ds_read_b64_tr_b16 v[170:171], v246 offset:61760
	ds_read_b64_tr_b16 v[172:173], v246 offset:62912
	v_add_u32_e32 v163, 0xe800, v246
	v_cvt_pk_bf16_f32 v48, v48, v49
	v_cvt_pk_bf16_f32 v49, v50, v51
	s_waitcnt lgkmcnt(2)
	v_mfma_f32_32x32x16_bf16 v[0:15], v[208:211], v[242:245], v[0:15]
	ds_read_b64_tr_b16 v[208:209], v246 offset:64000
	ds_read_b64_tr_b16 v[210:211], v246 offset:65152
	v_cvt_pk_bf16_f32 v50, v52, v53
	v_cvt_pk_bf16_f32 v51, v56, v57
	v_fma_f32 v33, v224, v252, -v229
	v_exp_f32_e32 v169, v33
	v_fma_f32 v33, v223, v252, -v229
	v_cvt_pk_bf16_f32 v38, v38, v39
	s_waitcnt lgkmcnt(2)
	v_mfma_f32_32x32x16_bf16 v[16:31], v[170:173], v[242:245], v[16:31]
	v_cvt_pk_bf16_f32 v170, v72, v73
	v_cvt_pk_bf16_f32 v171, v74, v75
	v_cvt_pk_bf16_f32 v172, v76, v77
	v_cvt_pk_bf16_f32 v173, v78, v79
	ds_read_b64_tr_b16 v[74:75], v246 offset:64064
	ds_read_b64_tr_b16 v[76:77], v246 offset:65216
	v_cvt_pk_bf16_f32 v78, v68, v69
	v_cvt_pk_bf16_f32 v79, v70, v71
	s_waitcnt lgkmcnt(2)
	v_mfma_f32_32x32x16_bf16 v[0:15], v[208:211], v[170:173], v[0:15]
	ds_read_b64_tr_b16 v[208:209], v163 offset:6912
	ds_read_b64_tr_b16 v[210:211], v163 offset:8064
	v_cvt_pk_bf16_f32 v39, v40, v41
	v_cvt_pk_bf16_f32 v40, v42, v43
	v_cvt_pk_bf16_f32 v41, v44, v45
	v_exp_f32_e32 v166, v33
	v_fma_f32 v33, v226, v252, -v229
	v_exp_f32_e32 v167, v33
	s_waitcnt lgkmcnt(2)
	v_mfma_f32_32x32x16_bf16 v[16:31], v[74:77], v[170:173], v[16:31]
	v_cvt_pk_bf16_f32 v76, v62, v63
	v_cvt_pk_bf16_f32 v77, v66, v67
	ds_read_b64_tr_b16 v[66:67], v163 offset:6976
	ds_read_b64_tr_b16 v[68:69], v163 offset:8128
	ds_read_b64_tr_b16 v[170:171], v163 offset:9216
	ds_read_b64_tr_b16 v[172:173], v163 offset:10368
	v_fma_f32 v33, v225, v252, -v229
	v_exp_f32_e32 v72, v33
	v_fma_f32 v33, v227, v252, -v229
	s_waitcnt lgkmcnt(4)
	v_mfma_f32_32x32x16_bf16 v[0:15], v[208:211], v[76:79], v[0:15]
	v_exp_f32_e32 v73, v33
	v_fma_f32 v33, v228, v252, -v229
	v_exp_f32_e32 v74, v33
	v_fma_f32 v33, v230, v252, -v229
	v_exp_f32_e32 v75, v33
	v_fma_f32 v33, v232, v252, -v229
	v_exp_f32_e32 v62, v33
	s_waitcnt lgkmcnt(2)
	v_mfma_f32_32x32x16_bf16 v[16:31], v[66:69], v[76:79], v[16:31]
	v_cvt_pk_bf16_f32 v66, v54, v55
	v_cvt_pk_bf16_f32 v67, v58, v59
	v_cvt_pk_bf16_f32 v68, v60, v61
	v_cvt_pk_bf16_f32 v69, v64, v65
	ds_read_b64_tr_b16 v[58:59], v163 offset:9280
	ds_read_b64_tr_b16 v[60:61], v163 offset:10432
	ds_read_b64_tr_b16 v[76:77], v163 offset:11520
	ds_read_b64_tr_b16 v[78:79], v163 offset:12672
	v_fma_f32 v33, v233, v252, -v229
	s_waitcnt lgkmcnt(4)
	v_mfma_f32_32x32x16_bf16 v[0:15], v[170:173], v[66:69], v[0:15]
	v_exp_f32_e32 v63, v33
	v_fma_f32 v33, v231, v252, -v229
	v_exp_f32_e32 v54, v33
	v_fma_f32 v33, v234, v252, -v229
	v_exp_f32_e32 v55, v33
	v_fma_f32 v33, v235, v252, -v229
	s_waitcnt lgkmcnt(2)
	v_mfma_f32_32x32x16_bf16 v[16:31], v[58:61], v[66:69], v[16:31]
	ds_read_b64_tr_b16 v[56:57], v163 offset:11584
	ds_read_b64_tr_b16 v[58:59], v163 offset:12736
	ds_read_b64_tr_b16 v[64:65], v163 offset:13824
	ds_read_b64_tr_b16 v[66:67], v163 offset:14976
	ds_read_b64_tr_b16 v[42:43], v163 offset:13888
	ds_read_b64_tr_b16 v[44:45], v163 offset:15040
	v_exp_f32_e32 v60, v33
	v_fma_f32 v33, v236, v252, -v229
	v_exp_f32_e32 v61, v33
	v_fma_f32 v33, v237, v252, -v229
	s_waitcnt lgkmcnt(6)
; #define LAS __attribute__((address_space(3)))
; #define MFMA32(a, b, c) __builtin_amdgcn_mfma_f32_32x32x16_bf16((a), (b), (c), 0, 0, 0)
; __device__ __forceinline__ unsigned cvtpk(float lo, float hi) { f32x2_t v = {lo, hi}; bf16x2_t b = __builtin_convertvector(v, bf16x2_t); return __builtin_bit_cast(unsigned, b); }
; __device__ __forceinline__ s16x4 lds_tr(const LAS unsigned char* p) { return __builtin_bit_cast(s16x4, __builtin_amdgcn_ds_read_tr16_b64_v4i16((LAS v4i16_t*)p)); }
; __device__ __forceinline__ void attnA_unit(LAS unsigned char* lds, const Args& A, int unit) {
;     ...
;                 for (int kt = 0; kt < 5; ++kt)
; #pragma unroll
;                     for (int ks = 0; ks < 2; ++ks) {
;                         const bf16x8 pf = pack_frag(S[kt], ks);
;                         const LAS unsigned char* vr = vr0 + (32 * kt + 16 * ks) * AST;
;                         const s16x4 a0 = lds_tr(vr), a1 = lds_tr(vr + 8 * AST), c0 = lds_tr(vr + 64), c1 = lds_tr(vr + 8 * AST + 64);
;                         o0 = MFMA32(__builtin_shufflevector(a0, a1, 0, 1, 2, 3, 4, 5, 6, 7), pf, o0);
;                         o1 = MFMA32(__builtin_shufflevector(c0, c1, 0, 1, 2, 3, 4, 5, 6, 7), pf, o1);
;                     }
;                 const float inv = 1.0f / ls;
;                 bf16* orow = Qrow + 4 * hh;
; #pragma unroll
;                 for (int g4 = 0; g4 < 4; ++g4) {
;                     u32x2 w; w.x = cvtpk(o0[4 * g4] * inv, o0[4 * g4 + 1] * inv); w.y = cvtpk(o0[4 * g4 + 2] * inv, o0[4 * g4 + 3] * inv); *(u32x2*)(orow + 8 * g4) = w;
;                     u32x2 z; z.x = cvtpk(o1[4 * g4] * inv, o1[4 * g4 + 1] * inv); z.y = cvtpk(o1[4 * g4 + 2] * inv, o1[4 * g4 + 3] * inv); *(u32x2*)(orow + 32 + 8 * g4) = z;
;                 }
;                 if (hh == 0) LSE[(size_t)((g * 4 + b) * 8 + h) * 8192 + pbase + i0 + ql] = mx + __builtin_amdgcn_logf(ls);
	v_mfma_f32_32x32x16_bf16 v[0:15], v[76:79], v[48:51], v[0:15]
	v_exp_f32_e32 v52, v33
	v_fma_f32 v33, v240, v252, -v229
	v_exp_f32_e32 v53, v33
	v_fma_f32 v33, v239, v252, -v229
	s_waitcnt lgkmcnt(4)
	v_mfma_f32_32x32x16_bf16 v[16:31], v[56:59], v[48:51], v[16:31]
	v_add_f32_e64 v56, v34, v46
	v_add_f32_e64 v57, v35, v47
	ds_read_b64_tr_b16 v[46:47], v163 offset:16128
	ds_read_b64_tr_b16 v[48:49], v163 offset:17280
	v_cvt_pk_bf16_f32 v34, v34, v35
	v_cvt_pk_bf16_f32 v35, v36, v37
	v_exp_f32_e32 v50, v33
	v_fma_f32 v33, v241, v252, -v229
	v_exp_f32_e32 v51, v33
	s_waitcnt lgkmcnt(4)
	v_mfma_f32_32x32x16_bf16 v[0:15], v[64:67], v[38:41], v[0:15]
	s_waitcnt lgkmcnt(2)
	v_mfma_f32_32x32x16_bf16 v[16:31], v[42:45], v[38:41], v[16:31]
	v_add_f32_e64 v42, v36, v56
	v_add_f32_e64 v43, v37, v57
	v_cvt_pk_bf16_f32 v36, v164, v165
	v_cvt_pk_bf16_f32 v37, v168, v169
	v_add_f32_e64 v42, v164, v42
	v_add_f32_e64 v43, v165, v43
	ds_read_b64_tr_b16 v[38:39], v163 offset:16192
	ds_read_b64_tr_b16 v[40:41], v163 offset:17344
	v_pk_add_f32 v[42:43], v[168:169], v[42:43]
	s_waitcnt lgkmcnt(2)
	v_mfma_f32_32x32x16_bf16 v[0:15], v[46:49], v[34:37], v[0:15]
	v_add_f32_e64 v42, v166, v42
	v_add_f32_e64 v43, v167, v43
	v_add_f32_e64 v42, v72, v42
	v_add_f32_e64 v43, v73, v43
	v_add_f32_e64 v46, v74, v42
	v_add_f32_e64 v47, v75, v43
	ds_read_b64_tr_b16 v[42:43], v163 offset:18432
	ds_read_b64_tr_b16 v[44:45], v163 offset:19584
	v_pk_add_f32 v[46:47], v[62:63], v[46:47]
	s_waitcnt lgkmcnt(2)
	v_mfma_f32_32x32x16_bf16 v[16:31], v[38:41], v[34:37], v[16:31]
	v_cvt_pk_bf16_f32 v34, v166, v167
	v_cvt_pk_bf16_f32 v35, v72, v73
	v_cvt_pk_bf16_f32 v36, v74, v75
	v_cvt_pk_bf16_f32 v37, v62, v63
	ds_read_b64_tr_b16 v[38:39], v163 offset:18496
	ds_read_b64_tr_b16 v[40:41], v163 offset:19648
	s_waitcnt lgkmcnt(2)
	v_mfma_f32_32x32x16_bf16 v[0:15], v[42:45], v[34:37], v[0:15]
	v_add_f32_e64 v42, v54, v46
	v_add_f32_e64 v43, v55, v47
	v_add_f32_e64 v42, v60, v42
	v_add_f32_e64 v43, v61, v43
	v_add_f32_e64 v42, v52, v42
	v_add_f32_e64 v43, v53, v43
	v_pk_add_f32 v[42:43], v[50:51], v[42:43]
	s_waitcnt lgkmcnt(0)
	v_mfma_f32_32x32x16_bf16 v[16:31], v[38:41], v[34:37], v[16:31]
	v_add_f32_e32 v33, v42, v43
	ds_bpermute_b32 v34, v238, v33
	ds_read_b64_tr_b16 v[42:43], v163 offset:20736
	ds_read_b64_tr_b16 v[44:45], v163 offset:21888
	ds_read_b64_tr_b16 v[46:47], v163 offset:20800
	ds_read_b64_tr_b16 v[48:49], v163 offset:21952
	v_cvt_pk_bf16_f32 v36, v54, v55
	v_cvt_pk_bf16_f32 v37, v60, v61
	s_waitcnt lgkmcnt(4)
	v_add_f32_e32 v34, v33, v34
	v_div_scale_f32 v33, s[22:23], v34, v34, 1.0
	v_rcp_f32_e32 v35, v33
	v_cvt_pk_bf16_f32 v38, v52, v53
	v_cvt_pk_bf16_f32 v39, v50, v51
	v_add3_u32 v40, v162, v144, v32
	v_ashrrev_i32_e32 v41, 31, v40
	s_waitcnt lgkmcnt(2)
	v_mfma_f32_32x32x16_bf16 v[0:15], v[42:45], v[36:39], v[0:15]
	v_lshlrev_b64 v[40:41], 7, v[40:41]
	s_waitcnt lgkmcnt(0)
	v_mfma_f32_32x32x16_bf16 v[16:31], v[46:49], v[36:39], v[16:31]
	v_fma_f32 v36, -v33, v35, 1.0
	v_fmac_f32_e32 v35, v36, v35
	v_div_scale_f32 v36, vcc, 1.0, v34, 1.0
	v_mul_f32_e32 v37, v36, v35
	v_fma_f32 v38, -v33, v37, v36
	v_fmac_f32_e32 v37, v38, v35
	v_fma_f32 v33, -v33, v37, v36
	v_div_fmas_f32 v33, v33, v35, v37
	v_div_fixup_f32 v36, v33, v34, 1.0
	v_pk_mul_f32 v[0:1], v[36:37], v[0:1] op_sel_hi:[0,1]
	v_pk_mul_f32 v[2:3], v[36:37], v[2:3] op_sel_hi:[0,1]
	v_lshl_add_u64 v[38:39], v[160:161], 0, v[40:41]
	v_cvt_pk_bf16_f32 v0, v0, v1
	v_cvt_pk_bf16_f32 v1, v2, v3
	global_store_dwordx2 v[38:39], v[0:1], off
	v_pk_mul_f32 v[0:1], v[36:37], v[16:17] op_sel_hi:[0,1]
	v_pk_mul_f32 v[2:3], v[36:37], v[18:19] op_sel_hi:[0,1]
	v_cvt_pk_bf16_f32 v0, v0, v1
	v_cvt_pk_bf16_f32 v1, v2, v3
	global_store_dwordx2 v[38:39], v[0:1], off offset:64
	v_pk_mul_f32 v[0:1], v[36:37], v[4:5] op_sel_hi:[0,1]
	v_pk_mul_f32 v[2:3], v[36:37], v[6:7] op_sel_hi:[0,1]
	v_cvt_pk_bf16_f32 v0, v0, v1
	v_cvt_pk_bf16_f32 v1, v2, v3
	global_store_dwordx2 v[38:39], v[0:1], off offset:16
	v_pk_mul_f32 v[0:1], v[36:37], v[20:21] op_sel_hi:[0,1]
	v_pk_mul_f32 v[2:3], v[36:37], v[22:23] op_sel_hi:[0,1]
	v_cvt_pk_bf16_f32 v0, v0, v1
	v_cvt_pk_bf16_f32 v1, v2, v3
	global_store_dwordx2 v[38:39], v[0:1], off offset:80
	v_pk_mul_f32 v[0:1], v[36:37], v[8:9] op_sel_hi:[0,1]
	v_pk_mul_f32 v[2:3], v[36:37], v[10:11] op_sel_hi:[0,1]
	v_cvt_pk_bf16_f32 v0, v0, v1
	v_cvt_pk_bf16_f32 v1, v2, v3
	global_store_dwordx2 v[38:39], v[0:1], off offset:32
	v_pk_mul_f32 v[0:1], v[36:37], v[24:25] op_sel_hi:[0,1]
	v_pk_mul_f32 v[2:3], v[36:37], v[26:27] op_sel_hi:[0,1]
	v_cvt_pk_bf16_f32 v0, v0, v1
	v_cvt_pk_bf16_f32 v1, v2, v3
	global_store_dwordx2 v[38:39], v[0:1], off offset:96
	v_pk_mul_f32 v[0:1], v[36:37], v[12:13] op_sel_hi:[0,1]
	v_pk_mul_f32 v[2:3], v[36:37], v[14:15] op_sel_hi:[0,1]
	v_cvt_pk_bf16_f32 v0, v0, v1
	v_cvt_pk_bf16_f32 v1, v2, v3
	global_store_dwordx2 v[38:39], v[0:1], off offset:48
	v_pk_mul_f32 v[0:1], v[36:37], v[28:29] op_sel_hi:[0,1]
	v_pk_mul_f32 v[2:3], v[36:37], v[30:31] op_sel_hi:[0,1]
	v_cvt_pk_bf16_f32 v0, v0, v1
	v_cvt_pk_bf16_f32 v1, v2, v3
	global_store_dwordx2 v[38:39], v[0:1], off offset:112
	s_and_saveexec_b64 s[22:23], s[6:7]
	s_cbranch_execz .LBB0_303
	v_log_f32_e32 v2, v34
	v_ashrrev_i32_e32 v33, 31, v32
	v_lshl_add_u64 v[0:1], v[32:33], 2, s[80:81]
	v_ashrrev_i32_e32 v163, 31, v162
	v_lshl_add_u64 v[0:1], v[162:163], 2, v[0:1]
	v_lshl_add_u64 v[0:1], v[0:1], 0, v[184:185]
	v_add_f32_e32 v2, v229, v2
	global_store_dword v[0:1], v2, off
